# combo10: combo8b + XCD-local barriers (per-XCD counter only, no L2 writeback) at the P4-P5, P5-P6 and P6-P1 seams, enabled at run time when blockIdx&7 maps one-to-one onto XCC ids (bitmask census), gl
# baseline (speedup 1.0000x reference)
; #define LAS __attribute__((address_space(3)))
; __device__ __forceinline__ unsigned xb_add(unsigned* p, unsigned v) { return __hip_atomic_fetch_add(p, v, __ATOMIC_RELAXED, __HIP_MEMORY_SCOPE_AGENT); }
; __device__ __forceinline__ unsigned xb_xcc_id() { return (unsigned)__builtin_amdgcn_s_getreg((3 << 11) | 20) & 0xFu; }
; __device__ __forceinline__ XcdBarrier xcd_barrier_post(unsigned* bar, volatile LAS unsigned* st) {
;     XcdBarrier b; b.bar = bar; b.x = xb_xcc_id(); b.st = st;
;     if (threadIdx.x == 0) (void)xb_add(&bar[XB_XCNT(b.x)], 1u);
;     return b;
; __global__ void __launch_bounds__(512, 2) mega_fwd(Args a) {
;     ...
;     volatile LAS unsigned* MISC = (volatile LAS unsigned*)(ldsl + MISC_OFF);
;     if (tid < 16) MISC[tid] = 0u;
;     __syncthreads();
;     const XcdBarrier xbar = xcd_barrier_post((unsigned*)(ws + WS_BAR), MISC);
_Z8mega_fwd4Args:
	s_mov_b32 s66, s2
	s_load_dword s33, s[0:1], 0x138
	s_load_dwordx2 s[10:11], s[0:1], 0x130
	s_load_dwordx8 s[68:75], s[0:1], 0x0
	s_load_dwordx4 s[88:91], s[0:1], 0xa0
	s_load_dwordx2 s[2:3], s[0:1], 0x20
	v_and_b32_e32 v190, 0x3ff, v0
	s_add_u32 s12, s0, 0x130
	v_mov_b32_e32 v1, v190
	s_addc_u32 s13, s1, 0
	s_nop 0
	v_readfirstlane_b32 s24, v1
	v_cmp_gt_i32_e32 vcc, 16, v1
	s_and_saveexec_b64 s[4:5], vcc
	v_lshl_add_u32 v2, v1, 2, 0
	v_add_u32_e32 v2, 0x26800, v2
	v_mov_b32_e32 v3, 0
	ds_write_b32 v2, v3
	s_or_b64 exec, exec, s[4:5]
	s_waitcnt lgkmcnt(0)
	s_add_u32 s4, s90, 0x2e80000
	s_addc_u32 s5, s91, 0
	v_writelane_b32 v252, s4, 0
	s_barrier
	s_nop 0
	v_writelane_b32 v252, s5, 1
	s_getreg_b32 s4, hwreg(HW_REG_XCC_ID, 0, 4)
	s_and_b32 s4, s4, 15
	v_writelane_b32 v252, s4, 2
	s_and_b32 s5, s66, 7
	s_lshl_b32 s5, s5, 2
	v_readlane_b32 s98, v252, 0
	v_readlane_b32 s99, v252, 1
	s_add_u32 s98, s98, 0x3520
	s_addc_u32 s99, s99, 0
	s_add_u32 s98, s98, s5
	s_addc_u32 s99, s99, 0
	s_lshl_b32 s5, 1, s4
	s_mov_b64 s[6:7], exec
	s_mov_b64 exec, 1
	v_mov_b32_e32 v250, s5
	v_mov_b32_e32 v251, 0
	global_atomic_or v251, v250, s[98:99]
	s_mov_b64 exec, s[6:7]
	v_cmp_eq_u32_e64 s[6:7], 0, v190
	s_mov_b64 s[4:5], exec
	s_nop 0
	v_writelane_b32 v252, s6, 3
	s_nop 1
	v_writelane_b32 v252, s7, 4
	s_and_b64 s[6:7], s[4:5], s[6:7]
	s_mov_b64 exec, s[6:7]
	s_cbranch_execz .LBB0_5
	s_mov_b64 s[6:7], exec
	v_mbcnt_lo_u32_b32 v2, s6, 0
	v_mbcnt_hi_u32_b32 v2, s7, v2
	v_cmp_eq_u32_e32 vcc, 0, v2
	s_and_b64 s[8:9], exec, vcc
	s_mov_b64 exec, s[8:9]
	s_cbranch_execz .LBB0_5
	v_readlane_b32 s8, v252, 2
	s_bcnt1_i32_b64 s6, s[6:7]
	s_lshl_b32 s8, s8, 8
	v_mov_b32_e32 v3, s6
	v_readlane_b32 s6, v252, 0
	v_mov_b32_e32 v2, s8
	v_readlane_b32 s7, v252, 1
	s_nop 4
	global_atomic_add v2, v3, s[6:7] offset:1024

; __device__ __forceinline__ unsigned xb_ld(unsigned* p)              { return __hip_atomic_load(p, __ATOMIC_RELAXED, __HIP_MEMORY_SCOPE_AGENT); }
; __device__ __forceinline__ unsigned xb_add(unsigned* p, unsigned v) { return __hip_atomic_fetch_add(p, v, __ATOMIC_RELAXED, __HIP_MEMORY_SCOPE_AGENT); }
; #define XB_SPIN(cond, bar) do { unsigned _sp = 0; while (cond) { __builtin_amdgcn_s_sleep(1); \
;     if ((++_sp & 255u) == 0u) { if (xb_ld(&(bar)[XB_TMO])) break; if (_sp > XB_SPIN_CAP) { atomicAdd(&(bar)[XB_TMO], 1u); break; } } } } while (0)
; __device__ __forceinline__ void xcd_barrier(const XcdBarrier& b) {
;     ...
;             __builtin_amdgcn_fence(__ATOMIC_ACQUIRE, "agent");
;             xb_add(&bar[XB_XGEN(bx)], 1u);
;             asm volatile("s_waitcnt vmcnt(0)" ::: "memory");
;         } else {
;             XB_SPIN(xb_ld(&bar[XB_XGEN(bx)]) == gen, bar);
;             __builtin_amdgcn_fence(__ATOMIC_ACQUIRE, "agent");
;             asm volatile("s_waitcnt vmcnt(0)" ::: "memory");
.Lxb0_go:
	v_readfirstlane_b32 s12, v9
	s_cmp_lg_u32 s12, 0
	s_cbranch_scc1 .Lxb0_moded
	s_add_u32 s10, s10, 0x3520
	s_addc_u32 s11, s11, 0
	global_load_dwordx4 v[10:13], v161, s[10:11] sc1
	global_load_dwordx4 v[4:7], v161, s[10:11] offset:16 sc1
	s_mov_b32 s12, 1
	s_mov_b32 s13, 0
	s_waitcnt vmcnt(0)
	v_readfirstlane_b32 s2, v10
	s_bcnt1_i32_b32 s3, s2
	s_cmp_eq_u32 s3, 1
	s_cselect_b32 s12, s12, 2
	s_or_b32 s13, s13, s2
	v_readfirstlane_b32 s2, v11
	s_bcnt1_i32_b32 s3, s2
	s_cmp_eq_u32 s3, 1
	s_cselect_b32 s12, s12, 2
	s_or_b32 s13, s13, s2
	v_readfirstlane_b32 s2, v12
	s_bcnt1_i32_b32 s3, s2
	s_cmp_eq_u32 s3, 1
	s_cselect_b32 s12, s12, 2
	s_or_b32 s13, s13, s2
	v_readfirstlane_b32 s2, v13
	s_bcnt1_i32_b32 s3, s2
	s_cmp_eq_u32 s3, 1
	s_cselect_b32 s12, s12, 2
	s_or_b32 s13, s13, s2
	v_readfirstlane_b32 s2, v4
	s_bcnt1_i32_b32 s3, s2
	s_cmp_eq_u32 s3, 1
	s_cselect_b32 s12, s12, 2
	s_or_b32 s13, s13, s2
	v_readfirstlane_b32 s2, v5
	s_bcnt1_i32_b32 s3, s2
	s_cmp_eq_u32 s3, 1
	s_cselect_b32 s12, s12, 2
	s_or_b32 s13, s13, s2
	v_readfirstlane_b32 s2, v6
	s_bcnt1_i32_b32 s3, s2
	s_cmp_eq_u32 s3, 1
	s_cselect_b32 s12, s12, 2
	s_or_b32 s13, s13, s2
	v_readfirstlane_b32 s2, v7
	s_bcnt1_i32_b32 s3, s2
	s_cmp_eq_u32 s3, 1
	s_cselect_b32 s12, s12, 2
	s_or_b32 s13, s13, s2
	s_cmp_eq_u32 s13, 0xff
	s_cselect_b32 s12, s12, 2
	v_mov_b32_e32 v9, s12
	ds_write_b32 v0, v9 offset:12
